# attention loop: K/V LDS-DMA loads use SGPR base + 32-bit lane offset (no 64-bit VALU address adds); V block-0 reads and DMA issue interleaved with last QK MFMAs; p0 exps spread over PV gaps
# speedup vs baseline: 1.0539x; 1.0226x over previous
; #define SBAR() __builtin_amdgcn_sched_barrier(0)
; #define PK4(P, BASE, OUT) do { u32x4 w = {cvtpk(P[BASE + 0], P[BASE + 1]), cvtpk(P[BASE + 2], P[BASE + 3]), cvtpk(P[BASE + 4], P[BASE + 5]), cvtpk(P[BASE + 6], P[BASE + 7])}; \
;     OUT = *reinterpret_cast<bf16x8*>(&w); } while (0)
; __device__ __forceinline__ void finishSM(f32x16& p0, f32x16& p1, float alpha, float& l_reg, bf16x8& pa0, bf16x8& pa1, bf16x8& pa2, bf16x8& pa3) {
;   for (int r = 0; r < 16; ++r) p1[r] = __builtin_amdgcn_exp2f(p1[r]);
;   float ps = 0; for (int r = 0; r < 16; ++r) ps += p0[r]; for (int r = 0; r < 16; ++r) ps += p1[r];
;   asm volatile("" : "+v"(ps));
;   l_reg = l_reg * alpha + ps;
;     ...
;   PK4(p0, 0, pa0); PK4(p0, 8, pa1); PK4(p1, 0, pa2); PK4(p1, 8, pa3);
;     ...
; }
; __device__ __forceinline__ void qkt(f32x16& p0, f32x16& p1, const bf16* Ks, const bf16x8* qr, int r32, int hi) {
;   p0 = f32x16{}; p1 = f32x16{};
;   for (int d0 = 0; d0 < 8; ++d0) { int cb = (d0 * 16 + hi * 8) * 2;
;     bf16x8 b0 = *reinterpret_cast<const bf16x8*>((const char*)Ks + KSWZ(r32, cb));
;     bf16x8 b1 = *reinterpret_cast<const bf16x8*>((const char*)Ks + KSWZ(32 + r32, cb));
;     p0 = __builtin_amdgcn_mfma_f32_32x32x16_bf16(b0, qr[d0], p0, 0, 0, 0);
;     p1 = __builtin_amdgcn_mfma_f32_32x32x16_bf16(b1, qr[d0], p1, 0, 0, 0); }
; }
; template <typename TQ> ...
;     ...
;   for (int j = 1; j + 1 < NT; j += 2) {
;     SBAR(); qkt(pB0, pB1, (const bf16*)(K_lds + (j & 3) * (int)SHM_K), qr, r32, hi);
;     finishSM(pA0, pA1, alA, l_reg, pa0, pa1, pa2, pa3); SBAR();
;     DMA_TILE(j + 2, (j + 2) & 3); SBAR();
;     pv_d0(o, vb0 + ((j - 1) & 3) * (int)SHM_V, pa0, pa1, pa2, pa3); partialSM<true>(pB0, pB1, m_reg, mnB, alB);
.LBB0_461:
	s_mov_b32 s40, s33
	s_addk_i32 s33, 0xc000
	s_and_b32 s42, s33, 0xc000
	s_add_i32 s33, s57, s42
	v_add_u32_e32 v84, s33, v178
	ds_read_b128 v[80:83], v84
	ds_read_b128 v[84:87], v84 offset:8192
	v_add_u32_e32 v202, s33, v179
	ds_read_b128 v[198:201], v202
	ds_read_b128 v[202:205], v202 offset:8192
	v_add_u32_e32 v206, s33, v181
	s_waitcnt lgkmcnt(3)
	v_mfma_f32_32x32x16_bf16 v[96:111], v[80:83], v[136:139], 0
	v_add_u32_e32 v214, s33, v182
	v_exp_f32_e32 v238, v64
	v_add_f32_e32 v64, 0, v196
	v_add_f32_e32 v64, v197, v64
	v_add_u32_e32 v222, s33, v183
	v_add_f32_e32 v64, v193, v64
	v_add_f32_e32 v64, v195, v64
	s_waitcnt lgkmcnt(2)
	v_mfma_f32_32x32x16_bf16 v[80:95], v[84:87], v[136:139], 0
	v_add_f32_e32 v64, v191, v64
	v_add_f32_e32 v64, v194, v64
	v_add_f32_e32 v64, v190, v64
	v_add_f32_e32 v64, v192, v64
	v_add_f32_e32 v64, v169, v64
	v_add_f32_e32 v64, v171, v64
	v_add_u32_e32 v226, s33, v184
	s_waitcnt lgkmcnt(1)
	v_mfma_f32_32x32x16_bf16 v[96:111], v[198:201], v[140:143], v[96:111]
	v_add_f32_e32 v64, v167, v64
	v_add_f32_e32 v64, v170, v64
	v_add_f32_e32 v64, v165, v64
	v_add_f32_e32 v64, v168, v64
	v_add_f32_e32 v64, v164, v64
	v_add_f32_e32 v64, v166, v64
	v_exp_f32_e32 v239, v68
	s_waitcnt lgkmcnt(0)
	v_mfma_f32_32x32x16_bf16 v[80:95], v[202:205], v[140:143], v[80:95]
	v_add_u32_e32 v202, s33, v180
	ds_read_b128 v[198:201], v202
	ds_read_b128 v[202:205], v202 offset:8192
	v_add_f32_e32 v64, v238, v64
	v_exp_f32_e32 v240, v69
	v_add_u32_e32 v234, s33, v185
	v_exp_f32_e32 v241, v70
	v_exp_f32_e32 v242, v71
	s_waitcnt lgkmcnt(1)
	v_mfma_f32_32x32x16_bf16 v[96:111], v[198:201], v[132:135], v[96:111]
	ds_read_b128 v[198:201], v206
	ds_read_b128 v[206:209], v206 offset:8192
	ds_read_b128 v[210:213], v214
	ds_read_b128 v[214:217], v214 offset:8192
	ds_read_b128 v[218:221], v222
	ds_read_b128 v[222:225], v222 offset:8192
	v_exp_f32_e32 v243, v76
	v_exp_f32_e32 v244, v77
	v_exp_f32_e32 v245, v78
	v_exp_f32_e32 v79, v79
	s_waitcnt lgkmcnt(6)
	v_mfma_f32_32x32x16_bf16 v[80:95], v[202:205], v[132:135], v[80:95]
	ds_read_b128 v[202:205], v226
	ds_read_b128 v[226:229], v226 offset:8192
	ds_read_b128 v[230:233], v234
	ds_read_b128 v[234:237], v234 offset:8192
	s_waitcnt lgkmcnt(9)
	v_mfma_f32_32x32x16_bf16 v[96:111], v[198:201], v[128:131], v[96:111]
	v_exp_f32_e32 v199, v65
	v_exp_f32_e32 v200, v66
	v_exp_f32_e32 v201, v67
	v_add_f32_e32 v64, v199, v64
	v_add_f32_e32 v64, v200, v64
	v_add_f32_e32 v64, v201, v64
	s_waitcnt lgkmcnt(8)
	v_mfma_f32_32x32x16_bf16 v[80:95], v[206:209], v[128:131], v[80:95]
	v_exp_f32_e32 v206, v72
	v_add_f32_e32 v64, v239, v64
	v_exp_f32_e32 v207, v73
	v_add_f32_e32 v64, v240, v64
	v_exp_f32_e32 v208, v74
	v_add_f32_e32 v64, v241, v64
	v_exp_f32_e32 v209, v75
	s_waitcnt lgkmcnt(7)
	v_mfma_f32_32x32x16_bf16 v[96:111], v[210:213], v[124:127], v[96:111]
	v_add_f32_e32 v64, v242, v64
	v_add_f32_e32 v64, v206, v64
	v_add_f32_e32 v64, v207, v64
	v_add_f32_e32 v64, v208, v64
	v_add_f32_e32 v64, v209, v64
	v_add_f32_e32 v64, v243, v64
	v_add_f32_e32 v64, v244, v64
	s_waitcnt lgkmcnt(6)
	v_mfma_f32_32x32x16_bf16 v[80:95], v[214:217], v[124:127], v[80:95]
	v_add_f32_e32 v64, v245, v64
	v_add_f32_e32 v198, v79, v64
	v_cvt_pk_bf16_f32 v64, v196, v197
	v_cvt_pk_bf16_f32 v65, v193, v195
	v_cvt_pk_bf16_f32 v66, v191, v194
	v_cvt_pk_bf16_f32 v67, v190, v192
	s_waitcnt lgkmcnt(5)
	v_mfma_f32_32x32x16_bf16 v[96:111], v[218:221], v[120:123], v[96:111]
	v_cvt_pk_bf16_f32 v68, v169, v171
	v_cvt_pk_bf16_f32 v69, v167, v170
	v_cvt_pk_bf16_f32 v70, v165, v168
	v_cvt_pk_bf16_f32 v71, v164, v166
	v_cvt_pk_bf16_f32 v72, v238, v199
	v_cvt_pk_bf16_f32 v73, v200, v201
	v_cvt_pk_bf16_f32 v74, v239, v240
	s_waitcnt lgkmcnt(4)
	v_mfma_f32_32x32x16_bf16 v[80:95], v[222:225], v[120:123], v[80:95]
	v_cvt_pk_bf16_f32 v75, v241, v242
	v_cvt_pk_bf16_f32 v76, v206, v207
	v_cvt_pk_bf16_f32 v77, v208, v209
	v_cvt_pk_bf16_f32 v78, v243, v244
	v_cvt_pk_bf16_f32 v79, v245, v79
	s_waitcnt lgkmcnt(3)
	v_mfma_f32_32x32x16_bf16 v[96:111], v[202:205], v[116:119], v[96:111]
	s_add_i32 s33, s40, 0x8000
	s_and_b32 s43, s33, 0xc000
	v_add_u32_e32 v199, s43, v176
	ds_read_b64_tr_b16 v[190:191], v199 offset:0
	ds_read_b64_tr_b16 v[192:193], v199 offset:0x800
	ds_read_b64_tr_b16 v[194:195], v199 offset:0x1000
	ds_read_b64_tr_b16 v[196:197], v199 offset:0x1800
	s_waitcnt lgkmcnt(6)
	v_mfma_f32_32x32x16_bf16 v[80:95], v[226:229], v[116:119], v[80:95]
	ds_read_b64_tr_b16 v[200:201], v199 offset:0x2000
	ds_read_b64_tr_b16 v[202:203], v199 offset:0x2800
	ds_read_b64_tr_b16 v[204:205], v199 offset:0x3000
	ds_read_b64_tr_b16 v[206:207], v199 offset:0x3800
	s_add_i32 s74, s40, 0x4000
	s_and_b32 s74, s74, 0xc000
	s_add_u32 s98, s38, s22
	s_addc_u32 s99, s39, s23
	s_add_i32 s41, s67, s74
	s_add_u32 s100, s38, s24
	s_addc_u32 s101, s39, s25
	s_mov_b32 m0, s41
	s_add_i32 s74, s72, s74
	global_load_lds_dwordx4 v156, s[98:99]
	s_waitcnt lgkmcnt(9)
	v_mfma_f32_32x32x16_bf16 v[96:111], v[230:233], v[112:115], v[96:111]
	s_add_i32 m0, s41, 0x2000
	s_nop 0
	global_load_lds_dwordx4 v158, s[98:99]
	s_mov_b32 m0, s74
	s_nop 0
	global_load_lds_dwordx4 v162, s[100:101]
	s_waitcnt lgkmcnt(8)
	v_mfma_f32_32x32x16_bf16 v[80:95], v[234:237], v[112:115], v[80:95]
	s_add_i32 m0, s74, 0x2000
	s_nop 0
	global_load_lds_dwordx4 v160, s[100:101]
	s_nop 0
	s_waitcnt lgkmcnt(6)
	v_mfma_f32_32x32x16_bf16 v[48:63], v[64:67], v[190:193], v[48:63]
	v_exp_f32_e32 v232, v96
	ds_read_b64_tr_b16 v[190:191], v199 offset:0x200
	ds_read_b64_tr_b16 v[192:193], v199 offset:0xa00
	s_waitcnt lgkmcnt(6)
; #define SBAR() __builtin_amdgcn_sched_barrier(0)
; template <bool FIXED>
; __device__ __forceinline__ void partialSM(f32x16& p0, f32x16& p1, float& m_reg, float& mn, float& alpha) {
;     ...
;   for (int r = 0; r < 16; ++r) p0[r] = __builtin_amdgcn_exp2f(p0[r]);
; template <int D0> __device__ __forceinline__ void pv_one(f32x16& od, int vb, bf16x8 pa0, bf16x8 pa1, bf16x8 pa2, bf16x8 pa3) {
;   const s16x4 l0 = tr_read<v_rd_off(D0, 0, 0)>(vb), h0 = tr_read<v_rd_off(D0, 0, 1)>(vb), l1 = tr_read<v_rd_off(D0, 1, 0)>(vb), h1 = tr_read<v_rd_off(D0, 1, 1)>(vb);
;   const s16x4 l2 = tr_read<v_rd_off(D0, 2, 0)>(vb), h2 = tr_read<v_rd_off(D0, 2, 1)>(vb), l3 = tr_read<v_rd_off(D0, 3, 0)>(vb), h3 = tr_read<v_rd_off(D0, 3, 1)>(vb);
;   asm volatile("s_waitcnt lgkmcnt(0)" ::: "memory"); SBAR();
;     ...
;   od = __builtin_amdgcn_mfma_f32_32x32x16_bf16(pa0, PK(l0, h0), od, 0, 0, 0);
;   od = __builtin_amdgcn_mfma_f32_32x32x16_bf16(pa1, PK(l1, h1), od, 0, 0, 0);
;   od = __builtin_amdgcn_mfma_f32_32x32x16_bf16(pa2, PK(l2, h2), od, 0, 0, 0);
;   od = __builtin_amdgcn_mfma_f32_32x32x16_bf16(pa3, PK(l3, h3), od, 0, 0, 0);
;     ...
; }
; __device__ __forceinline__ void pv_d0(f32x16* o, int vb, bf16x8 pa0, bf16x8 pa1, bf16x8 pa2, bf16x8 pa3) {
;   pv_one<0>(o[0], vb, pa0, pa1, pa2, pa3); pv_one<1>(o[1], vb, pa0, pa1, pa2, pa3); pv_one<2>(o[2], vb, pa0, pa1, pa2, pa3); pv_one<3>(o[3], vb, pa0, pa1, pa2, pa3);
; }
; template <typename TQ> ...
;     ...
;     SBAR(); qkt(pA0, pA1, (const bf16*)(K_lds + ((j + 1) & 3) * (int)SHM_K), qr, r32, hi);
;     finishSM(pB0, pB1, alB, l_reg, pa0, pa1, pa2, pa3); SBAR();
;     if (j + 3 < NT) { DMA_TILE(j + 3, (j + 3) & 3); } SBAR();
	v_mfma_f32_32x32x16_bf16 v[48:63], v[68:71], v[194:197], v[48:63]
	v_exp_f32_e32 v233, v97
	ds_read_b64_tr_b16 v[194:195], v199 offset:0x1200
	ds_read_b64_tr_b16 v[196:197], v199 offset:0x1a00
	s_waitcnt lgkmcnt(6)
	v_mfma_f32_32x32x16_bf16 v[48:63], v[72:75], v[200:203], v[48:63]
	v_exp_f32_e32 v234, v98
	ds_read_b64_tr_b16 v[200:201], v199 offset:0x2200
	ds_read_b64_tr_b16 v[202:203], v199 offset:0x2a00
	ds_read_b64_tr_b16 v[208:209], v199 offset:0x3200
	ds_read_b64_tr_b16 v[210:211], v199 offset:0x3a00
	s_waitcnt lgkmcnt(8)
	v_mfma_f32_32x32x16_bf16 v[48:63], v[76:79], v[204:207], v[48:63]
	v_exp_f32_e32 v235, v99
	s_waitcnt lgkmcnt(6)
	v_mfma_f32_32x32x16_bf16 v[32:47], v[64:67], v[190:193], v[32:47]
	v_exp_f32_e32 v236, v100
	ds_read_b64_tr_b16 v[190:191], v199 offset:0x400
	ds_read_b64_tr_b16 v[192:193], v199 offset:0xc00
	s_waitcnt lgkmcnt(6)
	v_mfma_f32_32x32x16_bf16 v[32:47], v[68:71], v[194:197], v[32:47]
	v_exp_f32_e32 v237, v101
	ds_read_b64_tr_b16 v[194:195], v199 offset:0x1400
	ds_read_b64_tr_b16 v[196:197], v199 offset:0x1c00
	s_waitcnt lgkmcnt(6)
	v_mfma_f32_32x32x16_bf16 v[32:47], v[72:75], v[200:203], v[32:47]
	v_exp_f32_e32 v238, v102
	ds_read_b64_tr_b16 v[200:201], v199 offset:0x2400
	ds_read_b64_tr_b16 v[202:203], v199 offset:0x2c00
	ds_read_b64_tr_b16 v[204:205], v199 offset:0x3400
	ds_read_b64_tr_b16 v[206:207], v199 offset:0x3c00
	s_waitcnt lgkmcnt(8)
	v_mfma_f32_32x32x16_bf16 v[32:47], v[76:79], v[208:211], v[32:47]
	v_exp_f32_e32 v239, v103
	v_exp_f32_e32 v240, v104
	s_waitcnt lgkmcnt(6)
	v_mfma_f32_32x32x16_bf16 v[16:31], v[64:67], v[190:193], v[16:31]
	v_exp_f32_e32 v241, v105
	ds_read_b64_tr_b16 v[190:191], v199 offset:0x600
	ds_read_b64_tr_b16 v[192:193], v199 offset:0xe00
	s_waitcnt lgkmcnt(6)
	v_mfma_f32_32x32x16_bf16 v[16:31], v[68:71], v[194:197], v[16:31]
	v_exp_f32_e32 v242, v106
	ds_read_b64_tr_b16 v[194:195], v199 offset:0x1600
	ds_read_b64_tr_b16 v[196:197], v199 offset:0x1e00
	s_waitcnt lgkmcnt(6)
	v_mfma_f32_32x32x16_bf16 v[16:31], v[72:75], v[200:203], v[16:31]
	v_exp_f32_e32 v243, v107
	ds_read_b64_tr_b16 v[200:201], v199 offset:0x2600
	ds_read_b64_tr_b16 v[202:203], v199 offset:0x2e00
	ds_read_b64_tr_b16 v[208:209], v199 offset:0x3600
	ds_read_b64_tr_b16 v[210:211], v199 offset:0x3e00
	s_waitcnt lgkmcnt(8)
	v_mfma_f32_32x32x16_bf16 v[16:31], v[76:79], v[204:207], v[16:31]
	v_exp_f32_e32 v244, v108
	s_waitcnt lgkmcnt(6)
	v_mfma_f32_32x32x16_bf16 v[0:15], v[64:67], v[190:193], v[0:15]
	v_exp_f32_e32 v245, v109
	s_waitcnt vmcnt(4)
	s_waitcnt lgkmcnt(4)
	v_mfma_f32_32x32x16_bf16 v[0:15], v[68:71], v[194:197], v[0:15]
	v_exp_f32_e32 v246, v110
	s_waitcnt lgkmcnt(2)
	v_mfma_f32_32x32x16_bf16 v[0:15], v[72:75], v[200:203], v[0:15]
	v_exp_f32_e32 v247, v111
	s_waitcnt lgkmcnt(0)
	s_barrier
	v_mfma_f32_32x32x16_bf16 v[0:15], v[76:79], v[208:211], v[0:15]
	s_and_b32 s40, s40, 0xc000
	s_add_i32 s40, s57, s40
	v_add_u32_e32 v68, s40, v178
	ds_read_b128 v[64:67], v68
	ds_read_b128 v[68:71], v68 offset:8192
	v_add_u32_e32 v194, s40, v179
	ds_read_b128 v[190:193], v194
	ds_read_b128 v[194:197], v194 offset:8192
	v_add_u32_e32 v199, s40, v181
	s_waitcnt lgkmcnt(3)
	v_mfma_f32_32x32x16_bf16 v[96:111], v[64:67], v[136:139], 0
	v_exp_f32_e32 v80, v80
	v_exp_f32_e32 v81, v81
	v_exp_f32_e32 v82, v82
	v_exp_f32_e32 v83, v83
	v_exp_f32_e32 v87, v87
	v_exp_f32_e32 v248, v93
	v_exp_f32_e32 v249, v94
	s_waitcnt lgkmcnt(2)
	v_mfma_f32_32x32x16_bf16 v[64:79], v[68:71], v[136:139], 0
	s_waitcnt lgkmcnt(1)
	v_mfma_f32_32x32x16_bf16 v[96:111], v[190:193], v[140:143], v[96:111]
	s_waitcnt lgkmcnt(0)
	v_mfma_f32_32x32x16_bf16 v[64:79], v[194:197], v[140:143], v[64:79]
	v_add_u32_e32 v194, s40, v180
	ds_read_b128 v[190:193], v194
	ds_read_b128 v[194:197], v194 offset:8192
	s_waitcnt lgkmcnt(1)
	v_mfma_f32_32x32x16_bf16 v[96:111], v[190:193], v[132:135], v[96:111]
	ds_read_b128 v[190:193], v199
	ds_read_b128 v[200:203], v199 offset:8192
	v_add_u32_e32 v199, s40, v182
	ds_read_b128 v[204:207], v199
	ds_read_b128 v[208:211], v199 offset:8192
	v_add_u32_e32 v199, s40, v183
	ds_read_b128 v[212:215], v199
	ds_read_b128 v[216:219], v199 offset:8192
	v_add_u32_e32 v199, s40, v184
	s_waitcnt lgkmcnt(6)
	v_mfma_f32_32x32x16_bf16 v[64:79], v[194:197], v[132:135], v[64:79]
	ds_read_b128 v[194:197], v199
	ds_read_b128 v[220:223], v199 offset:8192
	v_add_u32_e32 v199, s40, v185
	ds_read_b128 v[224:227], v199
	ds_read_b128 v[228:231], v199 offset:8192
	s_waitcnt lgkmcnt(9)
	v_mfma_f32_32x32x16_bf16 v[96:111], v[190:193], v[128:131], v[96:111]
	s_cmp_ge_u32 s73, s37
	s_cselect_b64 s[40:41], -1, 0
	s_and_b64 vcc, exec, s[40:41]
	s_cbranch_vccnz .LBB0_463
	s_add_i32 s74, s67, s43
	s_add_u32 s98, s38, s26
	s_addc_u32 s99, s39, s27
	s_mov_b32 m0, s74
	s_add_i32 s43, s72, s43
	global_load_lds_dwordx4 v156, s[98:99]
	s_add_u32 s100, s38, s28
	s_addc_u32 s101, s39, s29
	s_add_i32 m0, s74, 0x2000
	s_nop 0
	global_load_lds_dwordx4 v158, s[98:99]
	s_mov_b32 m0, s43
	s_nop 0
	global_load_lds_dwordx4 v162, s[100:101]
	s_add_i32 m0, s43, 0x2000
	s_nop 0
	global_load_lds_dwordx4 v160, s[100:101]
; __device__ __forceinline__ void finishSM(f32x16& p0, f32x16& p1, float alpha, float& l_reg, bf16x8& pa0, bf16x8& pa1, bf16x8& pa2, bf16x8& pa3) {
;   for (int r = 0; r < 16; ++r) p1[r] = __builtin_amdgcn_exp2f(p1[r]);
;   float ps = 0; for (int r = 0; r < 16; ++r) ps += p0[r]; for (int r = 0; r < 16; ++r) ps += p1[r];
;   asm volatile("" : "+v"(ps));
;   l_reg = l_reg * alpha + ps;
;     ...
;   PK4(p0, 0, pa0); PK4(p0, 8, pa1); PK4(p1, 0, pa2); PK4(p1, 8, pa3);
;     ...
; }
; __device__ __forceinline__ void qkt(f32x16& p0, f32x16& p1, const bf16* Ks, const bf16x8* qr, int r32, int hi) {
;   p0 = f32x16{}; p1 = f32x16{};
;   for (int d0 = 0; d0 < 8; ++d0) { int cb = (d0 * 16 + hi * 8) * 2;
;     bf16x8 b0 = *reinterpret_cast<const bf16x8*>((const char*)Ks + KSWZ(r32, cb));
;     bf16x8 b1 = *reinterpret_cast<const bf16x8*>((const char*)Ks + KSWZ(32 + r32, cb));
;     p0 = __builtin_amdgcn_mfma_f32_32x32x16_bf16(b0, qr[d0], p0, 0, 0, 0);
;     p1 = __builtin_amdgcn_mfma_f32_32x32x16_bf16(b1, qr[d0], p1, 0, 0, 0); }
; }
; __device__ __forceinline__ int v_st(int k, int c) { const int kk = k;
;   return ((kk >> 3) * 4 + (c >> 5)) * 512 + ((kk & 7) * 32 + (c & 31)) * 2; }
; __device__ __forceinline__ int v_rd_base(int lane) { return ((lane & 3) << 3) | (((lane >> 2) & 3) << 6) | (((lane >> 4) & 1) << 5) | (((lane >> 5) & 1) << 8); }
; template <int OFF> __device__ __forceinline__ s16x4 tr_read(int vb) {
;   s16x4 r; asm volatile("ds_read_b64_tr_b16 %0, %1 offset:%2" : "=&v"(r) : "v"(vb), "i"(OFF) : "memory"); return r;
; }
; template <int D0> __device__ __forceinline__ void pv_one(f32x16& od, int vb, bf16x8 pa0, bf16x8 pa1, bf16x8 pa2, bf16x8 pa3) {
;   const s16x4 l0 = tr_read<v_rd_off(D0, 0, 0)>(vb), h0 = tr_read<v_rd_off(D0, 0, 1)>(vb), l1 = tr_read<v_rd_off(D0, 1, 0)>(vb), h1 = tr_read<v_rd_off(D0, 1, 1)>(vb);
;   const s16x4 l2 = tr_read<v_rd_off(D0, 2, 0)>(vb), h2 = tr_read<v_rd_off(D0, 2, 1)>(vb), l3 = tr_read<v_rd_off(D0, 3, 0)>(vb), h3 = tr_read<v_rd_off(D0, 3, 1)>(vb);
;   asm volatile("s_waitcnt lgkmcnt(0)" ::: "memory"); SBAR();
;     ...
;   od = __builtin_amdgcn_mfma_f32_32x32x16_bf16(pa0, PK(l0, h0), od, 0, 0, 0);
;   od = __builtin_amdgcn_mfma_f32_32x32x16_bf16(pa1, PK(l1, h1), od, 0, 0, 0);
;   od = __builtin_amdgcn_mfma_f32_32x32x16_bf16(pa2, PK(l2, h2), od, 0, 0, 0);
;   od = __builtin_amdgcn_mfma_f32_32x32x16_bf16(pa3, PK(l3, h3), od, 0, 0, 0);
;     ...
; }
.LBB0_463:
	v_exp_f32_e32 v190, v84
	v_add_f32_e32 v84, 0, v232
	v_add_f32_e32 v84, v233, v84
	v_add_f32_e32 v84, v234, v84
	v_add_f32_e32 v84, v235, v84
	v_add_f32_e32 v84, v236, v84
	v_add_f32_e32 v84, v237, v84
	s_waitcnt lgkmcnt(8)
	v_mfma_f32_32x32x16_bf16 v[64:79], v[200:203], v[128:131], v[64:79]
	v_add_f32_e32 v84, v238, v84
	v_add_f32_e32 v84, v239, v84
	v_add_f32_e32 v84, v240, v84
	v_add_f32_e32 v84, v241, v84
	v_add_f32_e32 v84, v242, v84
	v_add_f32_e32 v84, v243, v84
	v_add_f32_e32 v84, v244, v84
	s_waitcnt lgkmcnt(7)
	v_mfma_f32_32x32x16_bf16 v[96:111], v[204:207], v[124:127], v[96:111]
	v_add_f32_e32 v84, v245, v84
	v_add_f32_e32 v84, v246, v84
	v_add_f32_e32 v84, v247, v84
	v_add_f32_e32 v84, v80, v84
	v_exp_f32_e32 v191, v85
	v_add_f32_e32 v84, v81, v84
	v_exp_f32_e32 v192, v86
	s_waitcnt lgkmcnt(6)
	v_mfma_f32_32x32x16_bf16 v[64:79], v[208:211], v[124:127], v[64:79]
	v_add_f32_e32 v84, v82, v84
	v_add_f32_e32 v84, v83, v84
	v_exp_f32_e32 v193, v88
	v_add_f32_e32 v84, v190, v84
	v_exp_f32_e32 v200, v89
	v_add_f32_e32 v84, v191, v84
	v_exp_f32_e32 v201, v90
	s_waitcnt lgkmcnt(5)
	v_mfma_f32_32x32x16_bf16 v[96:111], v[212:215], v[120:123], v[96:111]
	v_add_f32_e32 v84, v192, v84
	v_exp_f32_e32 v202, v91
	v_add_f32_e32 v84, v87, v84
	v_exp_f32_e32 v203, v92
	v_add_f32_e32 v84, v193, v84
	v_add_f32_e32 v84, v200, v84
	v_add_f32_e32 v84, v201, v84
	s_waitcnt lgkmcnt(4)
	v_mfma_f32_32x32x16_bf16 v[64:79], v[216:219], v[120:123], v[64:79]
	v_exp_f32_e32 v204, v95
	v_add_f32_e32 v84, v202, v84
	v_add_f32_e32 v84, v203, v84
	v_add_f32_e32 v84, v248, v84
	v_add_f32_e32 v84, v249, v84
	v_add_f32_e32 v199, v204, v84
	s_waitcnt lgkmcnt(3)
	v_mfma_f32_32x32x16_bf16 v[96:111], v[194:197], v[116:119], v[96:111]
	v_cvt_pk_bf16_f32 v92, v232, v233
	v_cvt_pk_bf16_f32 v93, v234, v235
	v_cvt_pk_bf16_f32 v94, v236, v237
	v_cvt_pk_bf16_f32 v95, v238, v239
	v_cvt_pk_bf16_f32 v88, v240, v241
	v_cvt_pk_bf16_f32 v89, v242, v243
	v_cvt_pk_bf16_f32 v90, v244, v245
	s_waitcnt lgkmcnt(2)
	v_mfma_f32_32x32x16_bf16 v[64:79], v[220:223], v[116:119], v[64:79]
	v_cvt_pk_bf16_f32 v91, v246, v247
	v_cvt_pk_bf16_f32 v84, v80, v81
	v_cvt_pk_bf16_f32 v85, v82, v83
	v_cvt_pk_bf16_f32 v86, v190, v191
	v_cvt_pk_bf16_f32 v87, v192, v87
	v_cvt_pk_bf16_f32 v80, v193, v200
	v_cvt_pk_bf16_f32 v81, v201, v202
	v_add_u32_e32 v250, s42, v176
	ds_read_b64_tr_b16 v[164:165], v250 offset:0
	ds_read_b64_tr_b16 v[166:167], v250 offset:0x800
	ds_read_b64_tr_b16 v[168:169], v250 offset:0x1000
	ds_read_b64_tr_b16 v[170:171], v250 offset:0x1800
	s_waitcnt lgkmcnt(5)
	v_mfma_f32_32x32x16_bf16 v[96:111], v[224:227], v[112:115], v[96:111]
	v_cvt_pk_bf16_f32 v82, v203, v248
	v_cvt_pk_bf16_f32 v83, v249, v204
	v_add_u32_e32 v204, s42, v176
	ds_read_b64_tr_b16 v[190:191], v204 offset:0x2000
	ds_read_b64_tr_b16 v[192:193], v204 offset:0x2800
	ds_read_b64_tr_b16 v[194:195], v204 offset:0x3000
	ds_read_b64_tr_b16 v[196:197], v204 offset:0x3800
	s_waitcnt lgkmcnt(8)
	v_mfma_f32_32x32x16_bf16 v[64:79], v[228:231], v[112:115], v[64:79]
	s_nop 0
	s_waitcnt lgkmcnt(6)
	v_mfma_f32_32x32x16_bf16 v[48:63], v[92:95], v[164:167], v[48:63]
	ds_read_b64_tr_b16 v[164:165], v204 offset:0x200
	ds_read_b64_tr_b16 v[166:167], v204 offset:0xa00
	s_waitcnt lgkmcnt(6)
	v_mfma_f32_32x32x16_bf16 v[48:63], v[88:91], v[168:171], v[48:63]
	ds_read_b64_tr_b16 v[168:169], v204 offset:0x1200
	ds_read_b64_tr_b16 v[170:171], v204 offset:0x1a00
	s_waitcnt lgkmcnt(6)
	v_mfma_f32_32x32x16_bf16 v[48:63], v[84:87], v[190:193], v[48:63]
	ds_read_b64_tr_b16 v[190:191], v204 offset:0x2200
	ds_read_b64_tr_b16 v[192:193], v204 offset:0x2a00
	ds_read_b64_tr_b16 v[200:201], v204 offset:0x3200
	ds_read_b64_tr_b16 v[202:203], v204 offset:0x3a00
	s_waitcnt lgkmcnt(8)
	v_mfma_f32_32x32x16_bf16 v[48:63], v[80:83], v[194:197], v[48:63]
	s_waitcnt lgkmcnt(6)
	v_mfma_f32_32x32x16_bf16 v[32:47], v[92:95], v[164:167], v[32:47]
	ds_read_b64_tr_b16 v[164:165], v204 offset:0x400
	ds_read_b64_tr_b16 v[166:167], v204 offset:0xc00
	s_waitcnt lgkmcnt(6)
	v_mfma_f32_32x32x16_bf16 v[32:47], v[88:91], v[168:171], v[32:47]
	ds_read_b64_tr_b16 v[168:169], v204 offset:0x1400
	ds_read_b64_tr_b16 v[170:171], v204 offset:0x1c00
	s_waitcnt lgkmcnt(6)
	v_mfma_f32_32x32x16_bf16 v[32:47], v[84:87], v[190:193], v[32:47]
	ds_read_b64_tr_b16 v[190:191], v204 offset:0x2400
	ds_read_b64_tr_b16 v[192:193], v204 offset:0x2c00
	ds_read_b64_tr_b16 v[194:195], v204 offset:0x3400
	ds_read_b64_tr_b16 v[196:197], v204 offset:0x3c00
	s_waitcnt lgkmcnt(8)
	v_mfma_f32_32x32x16_bf16 v[32:47], v[80:83], v[200:203], v[32:47]
	s_waitcnt lgkmcnt(6)
	v_mfma_f32_32x32x16_bf16 v[16:31], v[92:95], v[164:167], v[16:31]
	ds_read_b64_tr_b16 v[164:165], v204 offset:0x600
	ds_read_b64_tr_b16 v[166:167], v204 offset:0xe00
	s_waitcnt lgkmcnt(6)
	v_mfma_f32_32x32x16_bf16 v[16:31], v[88:91], v[168:171], v[16:31]
	ds_read_b64_tr_b16 v[168:169], v204 offset:0x1600
	ds_read_b64_tr_b16 v[170:171], v204 offset:0x1e00
	s_waitcnt lgkmcnt(6)
	v_mfma_f32_32x32x16_bf16 v[16:31], v[84:87], v[190:193], v[16:31]
	ds_read_b64_tr_b16 v[190:191], v204 offset:0x2600
	ds_read_b64_tr_b16 v[192:193], v204 offset:0x2e00
	ds_read_b64_tr_b16 v[200:201], v204 offset:0x3600
	ds_read_b64_tr_b16 v[202:203], v204 offset:0x3e00
	s_waitcnt lgkmcnt(8)
	v_mfma_f32_32x32x16_bf16 v[16:31], v[80:83], v[194:197], v[16:31]
	s_waitcnt lgkmcnt(6)
	v_mfma_f32_32x32x16_bf16 v[0:15], v[92:95], v[164:167], v[0:15]
	s_mov_b64 s[42:43], -1
	s_and_b64 vcc, exec, s[40:41]
	s_waitcnt lgkmcnt(4)
	v_mfma_f32_32x32x16_bf16 v[0:15], v[88:91], v[168:171], v[0:15]
	s_waitcnt lgkmcnt(2)
	v_mfma_f32_32x32x16_bf16 v[0:15], v[84:87], v[190:193], v[0:15]
	s_waitcnt lgkmcnt(0)
	v_mfma_f32_32x32x16_bf16 v[0:15], v[80:83], v[200:203], v[0:15]
	s_cbranch_vccz .LBB0_465
	s_waitcnt vmcnt(0)
	s_barrier
	s_mov_b64 s[42:43], 0

; #define SBAR() __builtin_amdgcn_sched_barrier(0)
; #define PK4(P, BASE, OUT) do { u32x4 w = {cvtpk(P[BASE + 0], P[BASE + 1]), cvtpk(P[BASE + 2], P[BASE + 3]), cvtpk(P[BASE + 4], P[BASE + 5]), cvtpk(P[BASE + 6], P[BASE + 7])}; \
;     OUT = *reinterpret_cast<bf16x8*>(&w); } while (0)
; __device__ __forceinline__ void finishSM(f32x16& p0, f32x16& p1, float alpha, float& l_reg, bf16x8& pa0, bf16x8& pa1, bf16x8& pa2, bf16x8& pa3) {
;   for (int r = 0; r < 16; ++r) p1[r] = __builtin_amdgcn_exp2f(p1[r]);
;   float ps = 0; for (int r = 0; r < 16; ++r) ps += p0[r]; for (int r = 0; r < 16; ++r) ps += p1[r];
;   asm volatile("" : "+v"(ps));
;   l_reg = l_reg * alpha + ps;
;     ...
;   PK4(p0, 0, pa0); PK4(p0, 8, pa1); PK4(p1, 0, pa2); PK4(p1, 8, pa3);
;     ...
; }
; __device__ __forceinline__ void qkt(f32x16& p0, f32x16& p1, const bf16* Ks, const bf16x8* qr, int r32, int hi) {
;   p0 = f32x16{}; p1 = f32x16{};
;   for (int d0 = 0; d0 < 8; ++d0) { int cb = (d0 * 16 + hi * 8) * 2;
;     bf16x8 b0 = *reinterpret_cast<const bf16x8*>((const char*)Ks + KSWZ(r32, cb));
;     bf16x8 b1 = *reinterpret_cast<const bf16x8*>((const char*)Ks + KSWZ(32 + r32, cb));
;     p0 = __builtin_amdgcn_mfma_f32_32x32x16_bf16(b0, qr[d0], p0, 0, 0, 0);
;     p1 = __builtin_amdgcn_mfma_f32_32x32x16_bf16(b1, qr[d0], p1, 0, 0, 0); }
; }
; template <typename TQ> ...
;     ...
;   for (int j = 1; j + 1 < NT; j += 2) {
;     SBAR(); qkt(pB0, pB1, (const bf16*)(K_lds + (j & 3) * (int)SHM_K), qr, r32, hi);
;     finishSM(pA0, pA1, alA, l_reg, pa0, pa1, pa2, pa3); SBAR();
;     DMA_TILE(j + 2, (j + 2) & 3); SBAR();
;     pv_d0(o, vb0 + ((j - 1) & 3) * (int)SHM_V, pa0, pa1, pa2, pa3); partialSM<true>(pB0, pB1, m_reg, mnB, alB);
.LBB0_1365:
	s_mov_b32 s40, s33
	s_addk_i32 s33, 0xc000
	s_and_b32 s42, s33, 0xc000
	s_add_i32 s33, s56, s42
	v_add_u32_e32 v84, s33, v178
	ds_read_b128 v[80:83], v84
	ds_read_b128 v[84:87], v84 offset:8192
	v_add_u32_e32 v202, s33, v179
	ds_read_b128 v[198:201], v202
	ds_read_b128 v[202:205], v202 offset:8192
	v_add_u32_e32 v206, s33, v181
	s_waitcnt lgkmcnt(3)
	v_mfma_f32_32x32x16_bf16 v[96:111], v[80:83], v[136:139], 0
	v_add_u32_e32 v214, s33, v182
	v_exp_f32_e32 v238, v64
	v_add_f32_e32 v64, 0, v196
	v_add_f32_e32 v64, v197, v64
	v_add_u32_e32 v222, s33, v183
	v_add_f32_e32 v64, v193, v64
	v_add_f32_e32 v64, v195, v64
	s_waitcnt lgkmcnt(2)
	v_mfma_f32_32x32x16_bf16 v[80:95], v[84:87], v[136:139], 0
	v_add_f32_e32 v64, v191, v64
	v_add_f32_e32 v64, v194, v64
	v_add_f32_e32 v64, v190, v64
	v_add_f32_e32 v64, v192, v64
	v_add_f32_e32 v64, v169, v64
	v_add_f32_e32 v64, v171, v64
	v_add_u32_e32 v226, s33, v184
	s_waitcnt lgkmcnt(1)
	v_mfma_f32_32x32x16_bf16 v[96:111], v[198:201], v[140:143], v[96:111]
	v_add_f32_e32 v64, v167, v64
	v_add_f32_e32 v64, v170, v64
	v_add_f32_e32 v64, v165, v64
	v_add_f32_e32 v64, v168, v64
	v_add_f32_e32 v64, v164, v64
	v_add_f32_e32 v64, v166, v64
	v_exp_f32_e32 v239, v68
	s_waitcnt lgkmcnt(0)
	v_mfma_f32_32x32x16_bf16 v[80:95], v[202:205], v[140:143], v[80:95]
	v_add_u32_e32 v202, s33, v180
	ds_read_b128 v[198:201], v202
	ds_read_b128 v[202:205], v202 offset:8192
	v_add_f32_e32 v64, v238, v64
	v_exp_f32_e32 v240, v69
	v_add_u32_e32 v234, s33, v185
	v_exp_f32_e32 v241, v70
	v_exp_f32_e32 v242, v71
	s_waitcnt lgkmcnt(1)
	v_mfma_f32_32x32x16_bf16 v[96:111], v[198:201], v[132:135], v[96:111]
	ds_read_b128 v[198:201], v206
	ds_read_b128 v[206:209], v206 offset:8192
	ds_read_b128 v[210:213], v214
	ds_read_b128 v[214:217], v214 offset:8192
	ds_read_b128 v[218:221], v222
	ds_read_b128 v[222:225], v222 offset:8192
	v_exp_f32_e32 v243, v76
	v_exp_f32_e32 v244, v77
	v_exp_f32_e32 v245, v78
	v_exp_f32_e32 v79, v79
	s_waitcnt lgkmcnt(6)
	v_mfma_f32_32x32x16_bf16 v[80:95], v[202:205], v[132:135], v[80:95]
	ds_read_b128 v[202:205], v226
	ds_read_b128 v[226:229], v226 offset:8192
	ds_read_b128 v[230:233], v234
	ds_read_b128 v[234:237], v234 offset:8192
	s_waitcnt lgkmcnt(9)
	v_mfma_f32_32x32x16_bf16 v[96:111], v[198:201], v[128:131], v[96:111]
	v_exp_f32_e32 v199, v65
	v_exp_f32_e32 v200, v66
	v_exp_f32_e32 v201, v67
	v_add_f32_e32 v64, v199, v64
	v_add_f32_e32 v64, v200, v64
	v_add_f32_e32 v64, v201, v64
	s_waitcnt lgkmcnt(8)
	v_mfma_f32_32x32x16_bf16 v[80:95], v[206:209], v[128:131], v[80:95]
	v_exp_f32_e32 v206, v72
	v_add_f32_e32 v64, v239, v64
	v_exp_f32_e32 v207, v73
	v_add_f32_e32 v64, v240, v64
	v_exp_f32_e32 v208, v74
	v_add_f32_e32 v64, v241, v64
	v_exp_f32_e32 v209, v75
	s_waitcnt lgkmcnt(7)
	v_mfma_f32_32x32x16_bf16 v[96:111], v[210:213], v[124:127], v[96:111]
	v_add_f32_e32 v64, v242, v64
	v_add_f32_e32 v64, v206, v64
	v_add_f32_e32 v64, v207, v64
	v_add_f32_e32 v64, v208, v64
	v_add_f32_e32 v64, v209, v64
	v_add_f32_e32 v64, v243, v64
	v_add_f32_e32 v64, v244, v64
	s_waitcnt lgkmcnt(6)
	v_mfma_f32_32x32x16_bf16 v[80:95], v[214:217], v[124:127], v[80:95]
	v_add_f32_e32 v64, v245, v64
	v_add_f32_e32 v198, v79, v64
	v_cvt_pk_bf16_f32 v64, v196, v197
	v_cvt_pk_bf16_f32 v65, v193, v195
	v_cvt_pk_bf16_f32 v66, v191, v194
	v_cvt_pk_bf16_f32 v67, v190, v192
	s_waitcnt lgkmcnt(5)
	v_mfma_f32_32x32x16_bf16 v[96:111], v[218:221], v[120:123], v[96:111]
	v_cvt_pk_bf16_f32 v68, v169, v171
	v_cvt_pk_bf16_f32 v69, v167, v170
	v_cvt_pk_bf16_f32 v70, v165, v168
	v_cvt_pk_bf16_f32 v71, v164, v166
	v_cvt_pk_bf16_f32 v72, v238, v199
	v_cvt_pk_bf16_f32 v73, v200, v201
	v_cvt_pk_bf16_f32 v74, v239, v240
	s_waitcnt lgkmcnt(4)
	v_mfma_f32_32x32x16_bf16 v[80:95], v[222:225], v[120:123], v[80:95]
	v_cvt_pk_bf16_f32 v75, v241, v242
	v_cvt_pk_bf16_f32 v76, v206, v207
	v_cvt_pk_bf16_f32 v77, v208, v209
	v_cvt_pk_bf16_f32 v78, v243, v244
	v_cvt_pk_bf16_f32 v79, v245, v79
	s_waitcnt lgkmcnt(3)
	v_mfma_f32_32x32x16_bf16 v[96:111], v[202:205], v[116:119], v[96:111]
	s_add_i32 s33, s40, 0x8000
	s_and_b32 s43, s33, 0xc000
	v_add_u32_e32 v199, s43, v176
	ds_read_b64_tr_b16 v[190:191], v199 offset:0
	ds_read_b64_tr_b16 v[192:193], v199 offset:0x800
	ds_read_b64_tr_b16 v[194:195], v199 offset:0x1000
	ds_read_b64_tr_b16 v[196:197], v199 offset:0x1800
	s_waitcnt lgkmcnt(6)
	v_mfma_f32_32x32x16_bf16 v[80:95], v[226:229], v[116:119], v[80:95]
	ds_read_b64_tr_b16 v[200:201], v199 offset:0x2000
	ds_read_b64_tr_b16 v[202:203], v199 offset:0x2800
	ds_read_b64_tr_b16 v[204:205], v199 offset:0x3000
	ds_read_b64_tr_b16 v[206:207], v199 offset:0x3800
	s_add_i32 s73, s40, 0x4000
	s_and_b32 s73, s73, 0xc000
	s_add_u32 s98, s38, s22
	s_addc_u32 s99, s39, s23
	s_add_i32 s41, s66, s73
	s_add_u32 s100, s38, s24
	s_addc_u32 s101, s39, s25
	s_mov_b32 m0, s41
	s_add_i32 s73, s67, s73
	global_load_lds_dwordx4 v156, s[98:99]
	s_waitcnt lgkmcnt(9)
	v_mfma_f32_32x32x16_bf16 v[96:111], v[230:233], v[112:115], v[96:111]
	s_add_i32 m0, s41, 0x2000
	s_nop 0
	global_load_lds_dwordx4 v158, s[98:99]
	s_mov_b32 m0, s73
	s_nop 0
	global_load_lds_dwordx4 v162, s[100:101]
	s_waitcnt lgkmcnt(8)
	v_mfma_f32_32x32x16_bf16 v[80:95], v[234:237], v[112:115], v[80:95]
	s_add_i32 m0, s73, 0x2000
	s_nop 0
	global_load_lds_dwordx4 v160, s[100:101]
	s_nop 0
	s_waitcnt lgkmcnt(6)
; #define SBAR() __builtin_amdgcn_sched_barrier(0)
; template <bool FIXED>
; __device__ __forceinline__ void partialSM(f32x16& p0, f32x16& p1, float& m_reg, float& mn, float& alpha) {
;     ...
;   for (int r = 0; r < 16; ++r) p0[r] = __builtin_amdgcn_exp2f(p0[r]);
; template <int D0> __device__ __forceinline__ void pv_one(f32x16& od, int vb, bf16x8 pa0, bf16x8 pa1, bf16x8 pa2, bf16x8 pa3) {
;   const s16x4 l0 = tr_read<v_rd_off(D0, 0, 0)>(vb), h0 = tr_read<v_rd_off(D0, 0, 1)>(vb), l1 = tr_read<v_rd_off(D0, 1, 0)>(vb), h1 = tr_read<v_rd_off(D0, 1, 1)>(vb);
;   const s16x4 l2 = tr_read<v_rd_off(D0, 2, 0)>(vb), h2 = tr_read<v_rd_off(D0, 2, 1)>(vb), l3 = tr_read<v_rd_off(D0, 3, 0)>(vb), h3 = tr_read<v_rd_off(D0, 3, 1)>(vb);
;   asm volatile("s_waitcnt lgkmcnt(0)" ::: "memory"); SBAR();
;     ...
;   od = __builtin_amdgcn_mfma_f32_32x32x16_bf16(pa0, PK(l0, h0), od, 0, 0, 0);
;   od = __builtin_amdgcn_mfma_f32_32x32x16_bf16(pa1, PK(l1, h1), od, 0, 0, 0);
;   od = __builtin_amdgcn_mfma_f32_32x32x16_bf16(pa2, PK(l2, h2), od, 0, 0, 0);
;   od = __builtin_amdgcn_mfma_f32_32x32x16_bf16(pa3, PK(l3, h3), od, 0, 0, 0);
;     ...
; }
; __device__ __forceinline__ void pv_d0(f32x16* o, int vb, bf16x8 pa0, bf16x8 pa1, bf16x8 pa2, bf16x8 pa3) {
;   pv_one<0>(o[0], vb, pa0, pa1, pa2, pa3); pv_one<1>(o[1], vb, pa0, pa1, pa2, pa3); pv_one<2>(o[2], vb, pa0, pa1, pa2, pa3); pv_one<3>(o[3], vb, pa0, pa1, pa2, pa3);
; }
; template <typename TQ> ...
;     ...
;     SBAR(); qkt(pA0, pA1, (const bf16*)(K_lds + ((j + 1) & 3) * (int)SHM_K), qr, r32, hi);
;     finishSM(pB0, pB1, alB, l_reg, pa0, pa1, pa2, pa3); SBAR();
;     if (j + 3 < NT) { DMA_TILE(j + 3, (j + 3) & 3); } SBAR();
	v_mfma_f32_32x32x16_bf16 v[48:63], v[64:67], v[190:193], v[48:63]
	v_exp_f32_e32 v232, v96
	ds_read_b64_tr_b16 v[190:191], v199 offset:0x200
	ds_read_b64_tr_b16 v[192:193], v199 offset:0xa00
	s_waitcnt lgkmcnt(6)
	v_mfma_f32_32x32x16_bf16 v[48:63], v[68:71], v[194:197], v[48:63]
	v_exp_f32_e32 v233, v97
	ds_read_b64_tr_b16 v[194:195], v199 offset:0x1200
	ds_read_b64_tr_b16 v[196:197], v199 offset:0x1a00
	s_waitcnt lgkmcnt(6)
	v_mfma_f32_32x32x16_bf16 v[48:63], v[72:75], v[200:203], v[48:63]
	v_exp_f32_e32 v234, v98
	ds_read_b64_tr_b16 v[200:201], v199 offset:0x2200
	ds_read_b64_tr_b16 v[202:203], v199 offset:0x2a00
	ds_read_b64_tr_b16 v[208:209], v199 offset:0x3200
	ds_read_b64_tr_b16 v[210:211], v199 offset:0x3a00
	s_waitcnt lgkmcnt(8)
	v_mfma_f32_32x32x16_bf16 v[48:63], v[76:79], v[204:207], v[48:63]
	v_exp_f32_e32 v235, v99
	s_waitcnt lgkmcnt(6)
	v_mfma_f32_32x32x16_bf16 v[32:47], v[64:67], v[190:193], v[32:47]
	v_exp_f32_e32 v236, v100
	ds_read_b64_tr_b16 v[190:191], v199 offset:0x400
	ds_read_b64_tr_b16 v[192:193], v199 offset:0xc00
	s_waitcnt lgkmcnt(6)
	v_mfma_f32_32x32x16_bf16 v[32:47], v[68:71], v[194:197], v[32:47]
	v_exp_f32_e32 v237, v101
	ds_read_b64_tr_b16 v[194:195], v199 offset:0x1400
	ds_read_b64_tr_b16 v[196:197], v199 offset:0x1c00
	s_waitcnt lgkmcnt(6)
	v_mfma_f32_32x32x16_bf16 v[32:47], v[72:75], v[200:203], v[32:47]
	v_exp_f32_e32 v238, v102
	ds_read_b64_tr_b16 v[200:201], v199 offset:0x2400
	ds_read_b64_tr_b16 v[202:203], v199 offset:0x2c00
	ds_read_b64_tr_b16 v[204:205], v199 offset:0x3400
	ds_read_b64_tr_b16 v[206:207], v199 offset:0x3c00
	s_waitcnt lgkmcnt(8)
	v_mfma_f32_32x32x16_bf16 v[32:47], v[76:79], v[208:211], v[32:47]
	v_exp_f32_e32 v239, v103
	v_exp_f32_e32 v240, v104
	s_waitcnt lgkmcnt(6)
	v_mfma_f32_32x32x16_bf16 v[16:31], v[64:67], v[190:193], v[16:31]
	v_exp_f32_e32 v241, v105
	ds_read_b64_tr_b16 v[190:191], v199 offset:0x600
	ds_read_b64_tr_b16 v[192:193], v199 offset:0xe00
	s_waitcnt lgkmcnt(6)
	v_mfma_f32_32x32x16_bf16 v[16:31], v[68:71], v[194:197], v[16:31]
	v_exp_f32_e32 v242, v106
	ds_read_b64_tr_b16 v[194:195], v199 offset:0x1600
	ds_read_b64_tr_b16 v[196:197], v199 offset:0x1e00
	s_waitcnt lgkmcnt(6)
	v_mfma_f32_32x32x16_bf16 v[16:31], v[72:75], v[200:203], v[16:31]
	v_exp_f32_e32 v243, v107
	ds_read_b64_tr_b16 v[200:201], v199 offset:0x2600
	ds_read_b64_tr_b16 v[202:203], v199 offset:0x2e00
	ds_read_b64_tr_b16 v[208:209], v199 offset:0x3600
	ds_read_b64_tr_b16 v[210:211], v199 offset:0x3e00
	s_waitcnt lgkmcnt(8)
	v_mfma_f32_32x32x16_bf16 v[16:31], v[76:79], v[204:207], v[16:31]
	v_exp_f32_e32 v244, v108
	s_waitcnt lgkmcnt(6)
	v_mfma_f32_32x32x16_bf16 v[0:15], v[64:67], v[190:193], v[0:15]
	v_exp_f32_e32 v245, v109
	s_waitcnt vmcnt(4)
	s_waitcnt lgkmcnt(4)
	v_mfma_f32_32x32x16_bf16 v[0:15], v[68:71], v[194:197], v[0:15]
	v_exp_f32_e32 v246, v110
	s_waitcnt lgkmcnt(2)
	v_mfma_f32_32x32x16_bf16 v[0:15], v[72:75], v[200:203], v[0:15]
	v_exp_f32_e32 v247, v111
	s_waitcnt lgkmcnt(0)
	s_barrier
	v_mfma_f32_32x32x16_bf16 v[0:15], v[76:79], v[208:211], v[0:15]
	s_and_b32 s40, s40, 0xc000
	s_add_i32 s40, s56, s40
	v_add_u32_e32 v68, s40, v178
	ds_read_b128 v[64:67], v68
	ds_read_b128 v[68:71], v68 offset:8192
	v_add_u32_e32 v194, s40, v179
	ds_read_b128 v[190:193], v194
	ds_read_b128 v[194:197], v194 offset:8192
	v_add_u32_e32 v199, s40, v181
	s_waitcnt lgkmcnt(3)
	v_mfma_f32_32x32x16_bf16 v[96:111], v[64:67], v[136:139], 0
	v_exp_f32_e32 v80, v80
	v_exp_f32_e32 v81, v81
	v_exp_f32_e32 v82, v82
	v_exp_f32_e32 v83, v83
	v_exp_f32_e32 v87, v87
	v_exp_f32_e32 v248, v93
	v_exp_f32_e32 v249, v94
	s_waitcnt lgkmcnt(2)
	v_mfma_f32_32x32x16_bf16 v[64:79], v[68:71], v[136:139], 0
	s_waitcnt lgkmcnt(1)
	v_mfma_f32_32x32x16_bf16 v[96:111], v[190:193], v[140:143], v[96:111]
	s_waitcnt lgkmcnt(0)
	v_mfma_f32_32x32x16_bf16 v[64:79], v[194:197], v[140:143], v[64:79]
	v_add_u32_e32 v194, s40, v180
	ds_read_b128 v[190:193], v194
	ds_read_b128 v[194:197], v194 offset:8192
	s_waitcnt lgkmcnt(1)
	v_mfma_f32_32x32x16_bf16 v[96:111], v[190:193], v[132:135], v[96:111]
	ds_read_b128 v[190:193], v199
	ds_read_b128 v[200:203], v199 offset:8192
	v_add_u32_e32 v199, s40, v182
	ds_read_b128 v[204:207], v199
	ds_read_b128 v[208:211], v199 offset:8192
	v_add_u32_e32 v199, s40, v183
	ds_read_b128 v[212:215], v199
	ds_read_b128 v[216:219], v199 offset:8192
	v_add_u32_e32 v199, s40, v184
	s_waitcnt lgkmcnt(6)
	v_mfma_f32_32x32x16_bf16 v[64:79], v[194:197], v[132:135], v[64:79]
	ds_read_b128 v[194:197], v199
	ds_read_b128 v[220:223], v199 offset:8192
	v_add_u32_e32 v199, s40, v185
	ds_read_b128 v[224:227], v199
	ds_read_b128 v[228:231], v199 offset:8192
	s_waitcnt lgkmcnt(9)
	v_mfma_f32_32x32x16_bf16 v[96:111], v[190:193], v[128:131], v[96:111]
	s_cmp_ge_u32 s72, s37
	s_cselect_b64 s[40:41], -1, 0
	s_and_b64 vcc, exec, s[40:41]
	s_cbranch_vccnz .LBB0_1367
	s_add_i32 s73, s66, s43
	s_add_u32 s98, s38, s26
	s_addc_u32 s99, s39, s27
	s_mov_b32 m0, s73
	s_add_i32 s43, s67, s43
	global_load_lds_dwordx4 v156, s[98:99]
	s_add_u32 s100, s38, s28
	s_addc_u32 s101, s39, s29
	s_add_i32 m0, s73, 0x2000
	s_nop 0
	global_load_lds_dwordx4 v158, s[98:99]
	s_mov_b32 m0, s43
	s_nop 0
	global_load_lds_dwordx4 v162, s[100:101]
	s_add_i32 m0, s43, 0x2000
	s_nop 0
	global_load_lds_dwordx4 v160, s[100:101]

; __global__ void __launch_bounds__(512, 2) hybrid_fwd(Params P0) {
;     extern __shared__ __attribute__((aligned(16))) unsigned char lds[];
	.amdhsa_kernel _Z10hybrid_fwd6Params
		.amdhsa_group_segment_fixed_size 0
		.amdhsa_private_segment_fixed_size 0
		.amdhsa_kernarg_size 464
		.amdhsa_user_sgpr_count 2
		.amdhsa_user_sgpr_dispatch_ptr 0
		.amdhsa_user_sgpr_queue_ptr 0
		.amdhsa_user_sgpr_kernarg_segment_ptr 1
		.amdhsa_user_sgpr_dispatch_id 0
		.amdhsa_user_sgpr_kernarg_preload_length 0
		.amdhsa_user_sgpr_kernarg_preload_offset 0
		.amdhsa_user_sgpr_private_segment_size 0
		.amdhsa_uses_dynamic_stack 0
		.amdhsa_enable_private_segment 0
		.amdhsa_system_sgpr_workgroup_id_x 1
		.amdhsa_system_sgpr_workgroup_id_y 0
		.amdhsa_system_sgpr_workgroup_id_z 0
		.amdhsa_system_sgpr_workgroup_info 0
		.amdhsa_system_vgpr_workitem_id 2
		.amdhsa_next_free_vgpr 256
		.amdhsa_next_free_sgpr 102
		.amdhsa_accum_offset 256
		.amdhsa_reserve_vcc 1
		.amdhsa_float_round_mode_32 0
		.amdhsa_float_round_mode_16_64 0
		.amdhsa_float_denorm_mode_32 3
		.amdhsa_float_denorm_mode_16_64 3
		.amdhsa_dx10_clamp 1
		.amdhsa_ieee_mode 1
		.amdhsa_fp16_overflow 0
		.amdhsa_tg_split 0
		.amdhsa_exception_fp_ieee_invalid_op 0
		.amdhsa_exception_fp_denorm_src 0
		.amdhsa_exception_fp_ieee_div_zero 0
		.amdhsa_exception_fp_ieee_overflow 0
		.amdhsa_exception_fp_ieee_underflow 0
		.amdhsa_exception_fp_ieee_inexact 0
		.amdhsa_exception_int_div_zero 0
	.end_amdhsa_kernel

; __global__ void __launch_bounds__(512, 2) hybrid_fwd(Params P0) {
;     extern __shared__ __attribute__((aligned(16))) unsigned char lds[];
amdhsa.kernels:
  - .agpr_count:     0
    .args:
      - .offset:         0
        .size:           208
        .value_kind:     by_value
      - .offset:         208
        .size:           4
        .value_kind:     hidden_block_count_x
      - .offset:         212
        .size:           4
        .value_kind:     hidden_block_count_y
      - .offset:         216
        .size:           4
        .value_kind:     hidden_block_count_z
      - .offset:         220
        .size:           2
        .value_kind:     hidden_group_size_x
      - .offset:         222
        .size:           2
        .value_kind:     hidden_group_size_y
      - .offset:         224
        .size:           2
        .value_kind:     hidden_group_size_z
      - .offset:         226
        .size:           2
        .value_kind:     hidden_remainder_x
      - .offset:         228
        .size:           2
        .value_kind:     hidden_remainder_y
      - .offset:         230
        .size:           2
        .value_kind:     hidden_remainder_z
      - .offset:         248
        .size:           8
        .value_kind:     hidden_global_offset_x
      - .offset:         256
        .size:           8
        .value_kind:     hidden_global_offset_y
      - .offset:         264
        .size:           8
        .value_kind:     hidden_global_offset_z
      - .offset:         272
        .size:           2
        .value_kind:     hidden_grid_dims
      - .offset:         296
        .size:           8
        .value_kind:     hidden_multigrid_sync_arg
      - .offset:         328
        .size:           4
        .value_kind:     hidden_dynamic_lds_size
    .group_segment_fixed_size: 0
    .kernarg_segment_align: 8
    .kernarg_segment_size: 464
    .language:       OpenCL C
    .language_version:
      - 2
      - 0
    .max_flat_workgroup_size: 512
    .name:           _Z10hybrid_fwd6Params
    .private_segment_fixed_size: 0
    .sgpr_count:     108
    .sgpr_spill_count: 15
    .symbol:         _Z10hybrid_fwd6Params.kd
    .uniform_work_group_size: 1
    .uses_dynamic_stack: false
    .vgpr_count:     256
    .vgpr_spill_count: 0
    .wavefront_size: 64
